# GEMM units: first K-loop body peeled with zero C operand on each accumulator's first MFMA; the 128 accumulator-clearing moves and the vmcnt drain before every unit removed
# speedup vs baseline: 1.0095x; 1.0095x over previous
; #define PG8_STAGE(bufoff, gbase, voff) do { _Pragma("unroll") for (int _i = 0; _i < 2; ++_i) \
;         __builtin_amdgcn_global_load_lds((const unsigned*)((const char*)(gbase) + (voff)[_i]), (LAS unsigned*)(lds + (bufoff) + ldsw + _i * 8192), 16, 0, 0); } while (0)
; #define PG8_LDA(dst, b, h) do { _Pragma("unroll") for (int m = 0; m < 4; ++m) _Pragma("unroll") for (int k = 0; k < 2; ++k) dst[m][k] = *(const LAS bf16x8*)(lds + PG8_SA(b, h) + aoff + m * 2048 + k * 1024); } while (0)
; #define PG8_LDB(dst, b, h) do { _Pragma("unroll") for (int n = 0; n < 2; ++n) _Pragma("unroll") for (int k = 0; k < 2; ++k) dst[n][k] = *(const LAS bf16x8*)(lds + PG8_SB(b, h) + boff + n * 2048 + k * 1024); } while (0)
; #define PG8_MMA(ai, bj, At, Bt) do { __builtin_amdgcn_s_setprio(1); _Pragma("unroll") for (int m = 0; m < 4; ++m) _Pragma("unroll") for (int n = 0; n < 2; ++n) _Pragma("unroll") for (int k = 0; k < 2; ++k) \
;         acc[ai][bj][m][n] = __builtin_amdgcn_mfma_f32_16x16x32_bf16(Bt[n][k], At[m][k], acc[ai][bj][m][n], 0, 0, 0); __builtin_amdgcn_s_setprio(0); } while (0)
; #define PG8_WAIT_V(n) asm volatile("s_waitcnt vmcnt(" #n ")" ::: "memory")
; #define PG8_WAIT_L(n) asm volatile("s_waitcnt lgkmcnt(" #n ")" ::: "memory")
; #define PG8_BAR __builtin_amdgcn_s_barrier()
; #define PG8_SCHED __builtin_amdgcn_sched_barrier(0)
; template <class Epi>
; __device__ __forceinline__ void gemm_phase(LAS unsigned char* lds, const Gemm g, const TabSched& S, const Epi& E) {
;     ...
;         for (int t = 0; t < nt; t += 2) {
;             const bool last = (t == nt - 2);
;             const char* a1 = cA + (size_t)(t + 1) * kstep;
;             const char* a2 = last ? nA : cA + (size_t)(t + 2) * kstep; const char* b2 = last ? nB : cB + (size_t)(t + 2) * kstep;
;             const char* a3 = a2 + kstep; const char* b3 = b2 + kstep;
;             PG8_LDB(B0, 0, 0); PG8_LDB(B1, 0, 1); PG8_SCHED; PG8_LDA(At, 0, 0); PG8_STAGE(PG8_SA(1, 1), a1 + hstep, voffA);
;             PG8_WAIT_V(8); PG8_WAIT_L(0); PG8_BAR; PG8_MMA(0, 0, At, B0); PG8_MMA(0, 1, At, B1); PG8_BAR; PG8_SCHED;
;             PG8_LDA(At, 0, 1); PG8_STAGE(PG8_SB(0, 0), b2, voffB); PG8_STAGE(PG8_SB(0, 1), b2 + hstep, voffB); PG8_STAGE(PG8_SA(0, 0), a2, voffA);
.LBB0_415:
	s_cmp_lt_i32 s13, 1
	s_cbranch_scc1 .LBB0_425
	s_and_b64 s[42:43], s[44:45], exec
	s_cselect_b32 s19, s9, s27
	s_cselect_b32 s42, s8, s26
	s_cselect_b32 s43, s11, s41
	s_cselect_b32 s46, s10, s40
	s_add_i32 s47, s13, -2
	s_add_u32 s48, s40, 0x100
	s_addc_u32 s49, s41, 0
	s_add_u32 s26, s26, 0x80
	s_addc_u32 s27, s27, 0
	s_mov_b32 s40, 0
	s_add_i32 s50, s40, 2
	s_add_u32 s51, s26, 0x80
	s_addc_u32 s41, s27, 0
	s_add_i32 s74, 0, 0x10000
	s_cmp_eq_u32 s47, s40
	s_cselect_b32 s41, s19, s41
	s_cselect_b32 s40, s42, s51
	s_cselect_b32 s73, s43, s49
	s_cselect_b32 s72, s46, s48
	s_add_i32 s51, 0, 0x14000
	v_add_u32_e32 v166, s74, v178
	v_add_u32_e32 v188, s51, v178
	ds_read_b128 v[136:139], v166
	ds_read_b128 v[140:143], v166 offset:1024
	ds_read_b128 v[162:165], v166 offset:2048
	ds_read_b128 v[166:169], v166 offset:3072
	ds_read_b128 v[170:173], v188
	ds_read_b128 v[174:177], v188 offset:1024
	ds_read_b128 v[184:187], v188 offset:2048
	ds_read_b128 v[188:191], v188 offset:3072
	s_add_u32 s76, s26, s36
	s_addc_u32 s77, s27, 0
	s_add_i32 m0, s54, 0xc000
	ds_read_b128 v[192:195], v183
	ds_read_b128 v[196:199], v183 offset:1024
	ds_read_b128 v[200:203], v183 offset:2048
	ds_read_b128 v[204:207], v183 offset:3072
	ds_read_b128 v[208:211], v183 offset:4096
	ds_read_b128 v[230:233], v183 offset:5120
	ds_read_b128 v[234:237], v183 offset:6144
	ds_read_b128 v[238:241], v183 offset:7168
	global_load_lds_dwordx4 v2, s[76:77]
	s_add_i32 m0, s54, 0xe000
	s_nop 0
	global_load_lds_dwordx4 v146, s[76:77]
	s_waitcnt vmcnt(8)
	s_waitcnt lgkmcnt(0)
	s_barrier
	s_setprio 1
	s_waitcnt lgkmcnt(0)
	v_mfma_f32_16x16x32_bf16 v[132:135], v[136:139], v[192:195], 0
	v_mfma_f32_16x16x32_bf16 v[128:131], v[162:165], v[192:195], 0
	v_mfma_f32_16x16x32_bf16 v[124:127], v[136:139], v[200:203], 0
	v_mfma_f32_16x16x32_bf16 v[120:123], v[162:165], v[200:203], 0
	v_mfma_f32_16x16x32_bf16 v[116:119], v[136:139], v[208:211], 0
	v_mfma_f32_16x16x32_bf16 v[112:115], v[162:165], v[208:211], 0
	v_mfma_f32_16x16x32_bf16 v[108:111], v[136:139], v[234:237], 0
	v_mfma_f32_16x16x32_bf16 v[104:107], v[162:165], v[234:237], 0
	v_mfma_f32_16x16x32_bf16 v[132:135], v[140:143], v[196:199], v[132:135]
	v_mfma_f32_16x16x32_bf16 v[128:131], v[166:169], v[196:199], v[128:131]
	v_mfma_f32_16x16x32_bf16 v[124:127], v[140:143], v[204:207], v[124:127]
	v_mfma_f32_16x16x32_bf16 v[120:123], v[166:169], v[204:207], v[120:123]
	v_mfma_f32_16x16x32_bf16 v[116:119], v[140:143], v[230:233], v[116:119]
	v_mfma_f32_16x16x32_bf16 v[112:115], v[166:169], v[230:233], v[112:115]
	v_mfma_f32_16x16x32_bf16 v[108:111], v[140:143], v[238:241], v[108:111]
	v_mfma_f32_16x16x32_bf16 v[104:107], v[166:169], v[238:241], v[104:107]
	s_setprio 0
	s_setprio 1
	v_mfma_f32_16x16x32_bf16 v[100:103], v[170:173], v[192:195], 0
	v_mfma_f32_16x16x32_bf16 v[96:99], v[184:187], v[192:195], 0
	v_mfma_f32_16x16x32_bf16 v[92:95], v[170:173], v[200:203], 0
	v_mfma_f32_16x16x32_bf16 v[88:91], v[184:187], v[200:203], 0
	v_mfma_f32_16x16x32_bf16 v[84:87], v[170:173], v[208:211], 0
	v_mfma_f32_16x16x32_bf16 v[80:83], v[184:187], v[208:211], 0
	v_mfma_f32_16x16x32_bf16 v[76:79], v[170:173], v[234:237], 0
	v_mfma_f32_16x16x32_bf16 v[72:75], v[184:187], v[234:237], 0
	v_mfma_f32_16x16x32_bf16 v[100:103], v[174:177], v[196:199], v[100:103]
	v_mfma_f32_16x16x32_bf16 v[96:99], v[188:191], v[196:199], v[96:99]
	v_mfma_f32_16x16x32_bf16 v[92:95], v[174:177], v[204:207], v[92:95]
	v_mfma_f32_16x16x32_bf16 v[88:91], v[188:191], v[204:207], v[88:91]
	v_mfma_f32_16x16x32_bf16 v[84:87], v[174:177], v[230:233], v[84:87]
	v_mfma_f32_16x16x32_bf16 v[80:83], v[188:191], v[230:233], v[80:83]
	v_mfma_f32_16x16x32_bf16 v[76:79], v[174:177], v[238:241], v[76:79]
	v_mfma_f32_16x16x32_bf16 v[72:75], v[188:191], v[238:241], v[72:75]
	s_setprio 0
	s_barrier
	s_add_i32 s74, s74, s53
	s_mov_b32 m0, s74
	s_mov_b32 s78, s72
	s_mov_b32 s79, s73
	ds_read_b128 v[192:195], v183 offset:16384
	ds_read_b128 v[196:199], v183 offset:17408
	ds_read_b128 v[200:203], v183 offset:18432
	ds_read_b128 v[204:207], v183 offset:19456
	ds_read_b128 v[208:211], v183 offset:20480
	ds_read_b128 v[230:233], v183 offset:21504
	ds_read_b128 v[234:237], v183 offset:22528
	ds_read_b128 v[238:241], v183 offset:23552
	global_load_lds_dwordx4 v144, s[72:73]
	s_add_i32 m0, s74, 0x2000
	s_add_u32 s72, s72, s36
	s_addc_u32 s73, s73, 0
	s_add_i32 s51, s51, s53
	global_load_lds_dwordx4 v148, s[78:79]
	s_mov_b32 m0, s51
	s_mov_b32 s82, s72
	s_mov_b32 s83, s73
	global_load_lds_dwordx4 v144, s[72:73]
	s_add_i32 m0, s51, 0x2000
	s_mov_b32 s80, s40
	s_mov_b32 s81, s41
	global_load_lds_dwordx4 v148, s[72:73]
	s_mov_b32 m0, s54
	s_nop 0
	global_load_lds_dwordx4 v2, s[40:41]
	s_mov_b32 m0, s55
	s_nop 0
	global_load_lds_dwordx4 v146, s[40:41]
	s_waitcnt vmcnt(8)
	s_waitcnt lgkmcnt(0)
	s_barrier
; #define PG8_STAGE(bufoff, gbase, voff) do { _Pragma("unroll") for (int _i = 0; _i < 2; ++_i) \
;         __builtin_amdgcn_global_load_lds((const unsigned*)((const char*)(gbase) + (voff)[_i]), (LAS unsigned*)(lds + (bufoff) + ldsw + _i * 8192), 16, 0, 0); } while (0)
; #define PG8_LDA(dst, b, h) do { _Pragma("unroll") for (int m = 0; m < 4; ++m) _Pragma("unroll") for (int k = 0; k < 2; ++k) dst[m][k] = *(const LAS bf16x8*)(lds + PG8_SA(b, h) + aoff + m * 2048 + k * 1024); } while (0)
; #define PG8_LDB(dst, b, h) do { _Pragma("unroll") for (int n = 0; n < 2; ++n) _Pragma("unroll") for (int k = 0; k < 2; ++k) dst[n][k] = *(const LAS bf16x8*)(lds + PG8_SB(b, h) + boff + n * 2048 + k * 1024); } while (0)
; #define PG8_MMA(ai, bj, At, Bt) do { __builtin_amdgcn_s_setprio(1); _Pragma("unroll") for (int m = 0; m < 4; ++m) _Pragma("unroll") for (int n = 0; n < 2; ++n) _Pragma("unroll") for (int k = 0; k < 2; ++k) \
;         acc[ai][bj][m][n] = __builtin_amdgcn_mfma_f32_16x16x32_bf16(Bt[n][k], At[m][k], acc[ai][bj][m][n], 0, 0, 0); __builtin_amdgcn_s_setprio(0); } while (0)
; #define PG8_WAIT_V(n) asm volatile("s_waitcnt vmcnt(" #n ")" ::: "memory")
; #define PG8_WAIT_L(n) asm volatile("s_waitcnt lgkmcnt(" #n ")" ::: "memory")
; #define PG8_BAR __builtin_amdgcn_s_barrier()
; #define PG8_SCHED __builtin_amdgcn_sched_barrier(0)
; template <class Epi>
; __device__ __forceinline__ void gemm_phase(LAS unsigned char* lds, const Gemm g, const TabSched& S, const Epi& E) {
;     ...
;             PG8_WAIT_V(8); PG8_WAIT_L(0); PG8_BAR; PG8_MMA(1, 0, At, B0); PG8_MMA(1, 1, At, B1); PG8_BAR; PG8_SCHED;
;             PG8_LDB(B0, 1, 0); PG8_LDB(B1, 1, 1); PG8_SCHED; PG8_LDA(At, 1, 0); PG8_STAGE(PG8_SA(0, 1), a2 + hstep, voffA);
;             PG8_WAIT_V(8); PG8_WAIT_L(0); PG8_BAR; PG8_MMA(0, 0, At, B0); PG8_MMA(0, 1, At, B1); PG8_BAR; PG8_SCHED;
	s_setprio 1
	s_waitcnt lgkmcnt(0)
	v_mfma_f32_16x16x32_bf16 v[68:71], v[136:139], v[192:195], 0
	v_mfma_f32_16x16x32_bf16 v[64:67], v[162:165], v[192:195], 0
	v_mfma_f32_16x16x32_bf16 v[60:63], v[136:139], v[200:203], 0
	v_mfma_f32_16x16x32_bf16 v[56:59], v[162:165], v[200:203], 0
	v_mfma_f32_16x16x32_bf16 v[52:55], v[136:139], v[208:211], 0
	v_mfma_f32_16x16x32_bf16 v[48:51], v[162:165], v[208:211], 0
	v_mfma_f32_16x16x32_bf16 v[44:47], v[136:139], v[234:237], 0
	v_mfma_f32_16x16x32_bf16 v[40:43], v[162:165], v[234:237], 0
	v_mfma_f32_16x16x32_bf16 v[68:71], v[140:143], v[196:199], v[68:71]
	v_mfma_f32_16x16x32_bf16 v[64:67], v[166:169], v[196:199], v[64:67]
	v_mfma_f32_16x16x32_bf16 v[60:63], v[140:143], v[204:207], v[60:63]
	v_mfma_f32_16x16x32_bf16 v[56:59], v[166:169], v[204:207], v[56:59]
	v_mfma_f32_16x16x32_bf16 v[52:55], v[140:143], v[230:233], v[52:55]
	v_mfma_f32_16x16x32_bf16 v[48:51], v[166:169], v[230:233], v[48:51]
	v_mfma_f32_16x16x32_bf16 v[44:47], v[140:143], v[238:241], v[44:47]
	v_mfma_f32_16x16x32_bf16 v[40:43], v[166:169], v[238:241], v[40:43]
	s_setprio 0
	s_setprio 1
	v_mfma_f32_16x16x32_bf16 v[36:39], v[170:173], v[192:195], 0
	v_mfma_f32_16x16x32_bf16 v[32:35], v[184:187], v[192:195], 0
	v_mfma_f32_16x16x32_bf16 v[28:31], v[170:173], v[200:203], 0
	v_mfma_f32_16x16x32_bf16 v[24:27], v[184:187], v[200:203], 0
	v_mfma_f32_16x16x32_bf16 v[20:23], v[170:173], v[208:211], 0
	v_mfma_f32_16x16x32_bf16 v[16:19], v[184:187], v[208:211], 0
	v_mfma_f32_16x16x32_bf16 v[12:15], v[170:173], v[234:237], 0
	v_mfma_f32_16x16x32_bf16 v[8:11], v[184:187], v[234:237], 0
	v_mfma_f32_16x16x32_bf16 v[36:39], v[174:177], v[196:199], v[36:39]
	v_mfma_f32_16x16x32_bf16 v[32:35], v[188:191], v[196:199], v[32:35]
	v_mfma_f32_16x16x32_bf16 v[28:31], v[174:177], v[204:207], v[28:31]
	v_mfma_f32_16x16x32_bf16 v[24:27], v[188:191], v[204:207], v[24:27]
	v_mfma_f32_16x16x32_bf16 v[20:23], v[174:177], v[230:233], v[20:23]
	v_mfma_f32_16x16x32_bf16 v[16:19], v[188:191], v[230:233], v[16:19]
	v_mfma_f32_16x16x32_bf16 v[12:15], v[174:177], v[238:241], v[12:15]
	v_mfma_f32_16x16x32_bf16 v[8:11], v[188:191], v[238:241], v[8:11]
	s_setprio 0
	s_barrier
	s_add_i32 s51, 0, 0x18000
	s_add_i32 s72, 0, 0x1c000
	v_add_u32_e32 v166, s51, v178
	v_add_u32_e32 v188, s72, v178
	ds_read_b128 v[136:139], v166
	ds_read_b128 v[140:143], v166 offset:1024
	ds_read_b128 v[162:165], v166 offset:2048
	ds_read_b128 v[166:169], v166 offset:3072
	ds_read_b128 v[170:173], v188
	ds_read_b128 v[174:177], v188 offset:1024
	ds_read_b128 v[184:187], v188 offset:2048
	ds_read_b128 v[188:191], v188 offset:3072
	s_add_u32 s40, s40, s36
	s_addc_u32 s41, s41, 0
	s_mov_b32 m0, s56
	ds_read_b128 v[192:195], v183 offset:32768
	ds_read_b128 v[196:199], v183 offset:33792
	ds_read_b128 v[200:203], v183 offset:34816
	ds_read_b128 v[204:207], v183 offset:35840
	ds_read_b128 v[208:211], v183 offset:36864
	ds_read_b128 v[230:233], v183 offset:37888
	ds_read_b128 v[234:237], v183 offset:38912
	ds_read_b128 v[238:241], v183 offset:39936
	global_load_lds_dwordx4 v2, s[40:41]
	s_mov_b32 m0, s57
	s_nop 0
	global_load_lds_dwordx4 v146, s[40:41]
	s_waitcnt vmcnt(8)
	s_waitcnt lgkmcnt(0)
	s_barrier
	s_setprio 1
	s_waitcnt lgkmcnt(0)
	v_mfma_f32_16x16x32_bf16 v[132:135], v[136:139], v[192:195], v[132:135]
	v_mfma_f32_16x16x32_bf16 v[128:131], v[162:165], v[192:195], v[128:131]
	v_mfma_f32_16x16x32_bf16 v[124:127], v[136:139], v[200:203], v[124:127]
	v_mfma_f32_16x16x32_bf16 v[120:123], v[162:165], v[200:203], v[120:123]
	v_mfma_f32_16x16x32_bf16 v[116:119], v[136:139], v[208:211], v[116:119]
	v_mfma_f32_16x16x32_bf16 v[112:115], v[162:165], v[208:211], v[112:115]
	v_mfma_f32_16x16x32_bf16 v[108:111], v[136:139], v[234:237], v[108:111]
	v_mfma_f32_16x16x32_bf16 v[104:107], v[162:165], v[234:237], v[104:107]
	v_mfma_f32_16x16x32_bf16 v[132:135], v[140:143], v[196:199], v[132:135]
	v_mfma_f32_16x16x32_bf16 v[128:131], v[166:169], v[196:199], v[128:131]
	v_mfma_f32_16x16x32_bf16 v[124:127], v[140:143], v[204:207], v[124:127]
	v_mfma_f32_16x16x32_bf16 v[120:123], v[166:169], v[204:207], v[120:123]
	v_mfma_f32_16x16x32_bf16 v[116:119], v[140:143], v[230:233], v[116:119]
	v_mfma_f32_16x16x32_bf16 v[112:115], v[166:169], v[230:233], v[112:115]
	v_mfma_f32_16x16x32_bf16 v[108:111], v[140:143], v[238:241], v[108:111]
	v_mfma_f32_16x16x32_bf16 v[104:107], v[166:169], v[238:241], v[104:107]
	s_setprio 0
	s_setprio 1
	v_mfma_f32_16x16x32_bf16 v[100:103], v[170:173], v[192:195], v[100:103]
	v_mfma_f32_16x16x32_bf16 v[96:99], v[184:187], v[192:195], v[96:99]
	v_mfma_f32_16x16x32_bf16 v[92:95], v[170:173], v[200:203], v[92:95]
	v_mfma_f32_16x16x32_bf16 v[88:91], v[184:187], v[200:203], v[88:91]
	v_mfma_f32_16x16x32_bf16 v[84:87], v[170:173], v[208:211], v[84:87]
	v_mfma_f32_16x16x32_bf16 v[80:83], v[184:187], v[208:211], v[80:83]
	v_mfma_f32_16x16x32_bf16 v[76:79], v[170:173], v[234:237], v[76:79]
	v_mfma_f32_16x16x32_bf16 v[72:75], v[184:187], v[234:237], v[72:75]
	v_mfma_f32_16x16x32_bf16 v[100:103], v[174:177], v[196:199], v[100:103]
	v_mfma_f32_16x16x32_bf16 v[96:99], v[188:191], v[196:199], v[96:99]
	v_mfma_f32_16x16x32_bf16 v[92:95], v[174:177], v[204:207], v[92:95]
	v_mfma_f32_16x16x32_bf16 v[88:91], v[188:191], v[204:207], v[88:91]
	v_mfma_f32_16x16x32_bf16 v[84:87], v[174:177], v[230:233], v[84:87]
	v_mfma_f32_16x16x32_bf16 v[80:83], v[188:191], v[230:233], v[80:83]
	v_mfma_f32_16x16x32_bf16 v[76:79], v[174:177], v[238:241], v[76:79]
	v_mfma_f32_16x16x32_bf16 v[72:75], v[188:191], v[238:241], v[72:75]
	s_setprio 0
	s_barrier
; #define PG8_STAGE(bufoff, gbase, voff) do { _Pragma("unroll") for (int _i = 0; _i < 2; ++_i) \
;         __builtin_amdgcn_global_load_lds((const unsigned*)((const char*)(gbase) + (voff)[_i]), (LAS unsigned*)(lds + (bufoff) + ldsw + _i * 8192), 16, 0, 0); } while (0)
; #define PG8_LDA(dst, b, h) do { _Pragma("unroll") for (int m = 0; m < 4; ++m) _Pragma("unroll") for (int k = 0; k < 2; ++k) dst[m][k] = *(const LAS bf16x8*)(lds + PG8_SA(b, h) + aoff + m * 2048 + k * 1024); } while (0)
; #define PG8_MMA(ai, bj, At, Bt) do { __builtin_amdgcn_s_setprio(1); _Pragma("unroll") for (int m = 0; m < 4; ++m) _Pragma("unroll") for (int n = 0; n < 2; ++n) _Pragma("unroll") for (int k = 0; k < 2; ++k) \
;         acc[ai][bj][m][n] = __builtin_amdgcn_mfma_f32_16x16x32_bf16(Bt[n][k], At[m][k], acc[ai][bj][m][n], 0, 0, 0); __builtin_amdgcn_s_setprio(0); } while (0)
; #define PG8_WAIT_V(n) asm volatile("s_waitcnt vmcnt(" #n ")" ::: "memory")
; #define PG8_WAIT_L(n) asm volatile("s_waitcnt lgkmcnt(" #n ")" ::: "memory")
; #define PG8_BAR __builtin_amdgcn_s_barrier()
; #define PG8_SCHED __builtin_amdgcn_sched_barrier(0)
; template <class Epi>
; __device__ __forceinline__ void gemm_phase(LAS unsigned char* lds, const Gemm g, const TabSched& S, const Epi& E) {
;     ...
;             PG8_LDA(At, 1, 1); PG8_STAGE(PG8_SB(1, 0), b3, voffB); PG8_STAGE(PG8_SB(1, 1), b3 + hstep, voffB); PG8_STAGE(PG8_SA(1, 0), a3, voffA);
;             PG8_WAIT_V(8); PG8_WAIT_L(0); PG8_BAR; PG8_MMA(1, 0, At, B0); PG8_MMA(1, 1, At, B1); PG8_BAR; PG8_SCHED;
;         }
	s_add_i32 s40, s51, s53
	s_add_i32 m0, s40, 0xffffff80
	ds_read_b128 v[192:195], v183 offset:49152
	ds_read_b128 v[196:199], v183 offset:50176
	ds_read_b128 v[200:203], v183 offset:51200
	ds_read_b128 v[204:207], v183 offset:52224
	ds_read_b128 v[208:211], v183 offset:53248
	ds_read_b128 v[230:233], v183 offset:54272
	ds_read_b128 v[234:237], v183 offset:55296
	ds_read_b128 v[238:241], v183 offset:56320
	global_load_lds_dwordx4 v144, s[78:79] offset:128
	s_add_i32 m0, s40, 0x1f80
	s_add_i32 s40, s72, s53
	global_load_lds_dwordx4 v148, s[78:79] offset:128
	s_add_i32 m0, s40, 0xffffff80
	s_nop 0
	global_load_lds_dwordx4 v144, s[82:83] offset:128
	s_add_i32 m0, s40, 0x1f80
	s_nop 0
	global_load_lds_dwordx4 v148, s[82:83] offset:128
	s_add_i32 m0, s58, 0xffffff80
	s_nop 0
	global_load_lds_dwordx4 v2, s[80:81] offset:128
	s_add_i32 m0, s59, 0xffffff80
	s_nop 0
	global_load_lds_dwordx4 v146, s[80:81] offset:128
	s_waitcnt vmcnt(8)
	s_waitcnt lgkmcnt(0)
	s_barrier
	s_setprio 1
	s_waitcnt lgkmcnt(0)
	v_mfma_f32_16x16x32_bf16 v[68:71], v[136:139], v[192:195], v[68:71]
	v_mfma_f32_16x16x32_bf16 v[64:67], v[162:165], v[192:195], v[64:67]
	v_mfma_f32_16x16x32_bf16 v[60:63], v[136:139], v[200:203], v[60:63]
	v_mfma_f32_16x16x32_bf16 v[56:59], v[162:165], v[200:203], v[56:59]
	v_mfma_f32_16x16x32_bf16 v[52:55], v[136:139], v[208:211], v[52:55]
	v_mfma_f32_16x16x32_bf16 v[48:51], v[162:165], v[208:211], v[48:51]
	v_mfma_f32_16x16x32_bf16 v[44:47], v[136:139], v[234:237], v[44:47]
	v_mfma_f32_16x16x32_bf16 v[40:43], v[162:165], v[234:237], v[40:43]
	v_mfma_f32_16x16x32_bf16 v[68:71], v[140:143], v[196:199], v[68:71]
	v_mfma_f32_16x16x32_bf16 v[64:67], v[166:169], v[196:199], v[64:67]
	v_mfma_f32_16x16x32_bf16 v[60:63], v[140:143], v[204:207], v[60:63]
	v_mfma_f32_16x16x32_bf16 v[56:59], v[166:169], v[204:207], v[56:59]
	v_mfma_f32_16x16x32_bf16 v[52:55], v[140:143], v[230:233], v[52:55]
	v_mfma_f32_16x16x32_bf16 v[48:51], v[166:169], v[230:233], v[48:51]
	v_mfma_f32_16x16x32_bf16 v[44:47], v[140:143], v[238:241], v[44:47]
	v_mfma_f32_16x16x32_bf16 v[40:43], v[166:169], v[238:241], v[40:43]
	s_setprio 0
	s_setprio 1
	v_mfma_f32_16x16x32_bf16 v[36:39], v[170:173], v[192:195], v[36:39]
	v_mfma_f32_16x16x32_bf16 v[32:35], v[184:187], v[192:195], v[32:35]
	v_mfma_f32_16x16x32_bf16 v[28:31], v[170:173], v[200:203], v[28:31]
	v_mfma_f32_16x16x32_bf16 v[24:27], v[184:187], v[200:203], v[24:27]
	v_mfma_f32_16x16x32_bf16 v[20:23], v[170:173], v[208:211], v[20:23]
	v_mfma_f32_16x16x32_bf16 v[16:19], v[184:187], v[208:211], v[16:19]
	v_mfma_f32_16x16x32_bf16 v[12:15], v[170:173], v[234:237], v[12:15]
	v_mfma_f32_16x16x32_bf16 v[8:11], v[184:187], v[234:237], v[8:11]
	v_mfma_f32_16x16x32_bf16 v[36:39], v[174:177], v[196:199], v[36:39]
	v_mfma_f32_16x16x32_bf16 v[32:35], v[188:191], v[196:199], v[32:35]
	v_mfma_f32_16x16x32_bf16 v[28:31], v[174:177], v[204:207], v[28:31]
	v_mfma_f32_16x16x32_bf16 v[24:27], v[188:191], v[204:207], v[24:27]
	v_mfma_f32_16x16x32_bf16 v[20:23], v[174:177], v[230:233], v[20:23]
	v_mfma_f32_16x16x32_bf16 v[16:19], v[188:191], v[230:233], v[16:19]
	v_mfma_f32_16x16x32_bf16 v[12:15], v[174:177], v[238:241], v[12:15]
	v_mfma_f32_16x16x32_bf16 v[8:11], v[188:191], v[238:241], v[8:11]
	s_setprio 0
	s_barrier
	s_add_u32 s48, s48, 0x100
	s_addc_u32 s49, s49, 0
	s_add_u32 s26, s26, 0x100
	s_addc_u32 s27, s27, 0
	s_cmp_ge_i32 s50, s13
	s_mov_b32 s40, s50
	s_cbranch_scc1 .Lk1_exit

; #define PG8_BAR __builtin_amdgcn_s_barrier()
; template <class Epi>
; __device__ __forceinline__ void gemm_phase(LAS unsigned char* lds, const Gemm g, const TabSched& S, const Epi& E) {
;     ...
;         if (wr == 0) PG8_BAR;
.Lk1_exit:
	s_and_b64 vcc, exec, s[6:7]
	s_cbranch_vccz .LBB0_420
